# pair-decay scan + relaxed counted LDS waits (b,r of a step's inputs waited for just before their first readers)
# speedup vs baseline: 1.0107x; 1.0032x over previous
; __device__ __forceinline__ void scan_chain(const Params& p, int l, int chain, unsigned char* lds) {
;     ...
;             auto ld = [&](int s, StepIn& I) {
;                 const int ts = dir == 0 ? s : 31 - s; const float* ap = arr + ts * 64 + 8 * cgp;
;                 I.w0 = *(const f32x4*)(ap); I.w1 = *(const f32x4*)(ap + 4); I.k0 = *(const f32x4*)(ap + 2048); I.k1 = *(const f32x4*)(ap + 2048 + 4);
;                 I.a0 = *(const f32x4*)(ap + 4096); I.a1 = *(const f32x4*)(ap + 4096 + 4); I.b0 = *(const f32x4*)(ap + 6144); I.b1 = *(const f32x4*)(ap + 6144 + 4);
;                 I.r0 = *(const f32x4*)(ap + 8192); I.r1 = *(const f32x4*)(ap + 8192 + 4);
;                 I.v0 = arr[5 * 2048 + ts * 64 + i0]; I.v1 = arr[5 * 2048 + ts * 64 + i1];
;             };
;             auto comp = [&](int s, const StepIn& I) {
;                 const int ts = dir == 0 ? s : 31 - s;
;                 const f32x2 w[4] = {{I.w0[0], I.w0[1]}, {I.w0[2], I.w0[3]}, {I.w1[0], I.w1[1]}, {I.w1[2], I.w1[3]}};
;                 const f32x2 k[4] = {{I.k0[0], I.k0[1]}, {I.k0[2], I.k0[3]}, {I.k1[0], I.k1[1]}, {I.k1[2], I.k1[3]}};
;                 const f32x2 a[4] = {{I.a0[0], I.a0[1]}, {I.a0[2], I.a0[3]}, {I.a1[0], I.a1[1]}, {I.a1[2], I.a1[3]}};
;                 const f32x2 bb[4] = {{I.b0[0], I.b0[1]}, {I.b0[2], I.b0[3]}, {I.b1[0], I.b1[1]}, {I.b1[2], I.b1[3]}};
;                 const f32x2 r[4] = {{I.r0[0], I.r0[1]}, {I.r0[2], I.r0[3]}, {I.r1[0], I.r1[1]}, {I.r1[2], I.r1[3]}};
;                 f32x2 d0 = S0[0] * a[0] + S0[1] * a[1], d0b = S0[2] * a[2] + S0[3] * a[3];
;                 f32x2 d1 = S1[0] * a[0] + S1[1] * a[1], d1b = S1[2] * a[2] + S1[3] * a[3];
;                 d0 += d0b; d1 += d1b;
;                 const float sa0 = sum8(d0.x + d0.y), sa1 = sum8(d1.x + d1.y);
; #pragma unroll
;                 for (int e = 0; e < 4; ++e) { S0[e] = S0[e] * w[e] + bb[e] * sa0 + k[e] * I.v0; S1[e] = S1[e] * w[e] + bb[e] * sa1 + k[e] * I.v1; }
;                 f32x2 y0 = S0[0] * r[0] + S0[1] * r[1], y0b = S0[2] * r[2] + S0[3] * r[3];
;                 f32x2 y1 = S1[0] * r[0] + S1[1] * r[1], y1b = S1[2] * r[2] + S1[3] * r[3];
;                 y0 += y0b; y1 += y1b;
;                 const float ya = sum8(y0.x + y0.y), yb = sum8(y1.x + y1.y);
;                 if (cgp == 0) { yl[ts * 64 + i0] = ya; yl[ts * 64 + i1] = yb; }
;             };
.Lscan_iter:
	s_cmp_eq_u32 s2, 1
	s_cselect_b32 s13, 0, s7
	s_waitcnt lgkmcnt(4)
	v_pk_mul_f32 v[166:167], v[210:211], v[78:79] op_sel_hi:[1,0]
	ds_read_b128 v[118:121], v18 offset:16384
	v_pk_fma_f32 v[166:167], v[212:213], v[78:79], v[166:167] op_sel:[0,1,0]
	ds_read_b128 v[122:125], v18 offset:16400
	ds_read_b128 v[110:113], v18 offset:8192
	v_pk_fma_f32 v[166:167], v[214:215], v[80:81], v[166:167] op_sel_hi:[1,0,1]
	ds_read_b128 v[114:117], v18 offset:8208
	v_pk_fma_f32 v[166:167], v[216:217], v[80:81], v[166:167] op_sel:[0,1,0]
	ds_read2_b32 v[144:145], v19 offset1:8
	ds_read_b128 v[102:105], v18
	v_pk_fma_f32 v[166:167], v[218:219], v[82:83], v[166:167] op_sel_hi:[1,0,1]
	ds_read_b128 v[106:109], v18 offset:16
	v_pk_fma_f32 v[166:167], v[220:221], v[82:83], v[166:167] op_sel:[0,1,0]
	ds_read_b128 v[126:129], v18 offset:24576
	ds_read_b128 v[130:133], v18 offset:24592
	v_pk_fma_f32 v[166:167], v[222:223], v[84:85], v[166:167] op_sel_hi:[1,0,1]
	ds_read_b128 v[134:137], v18 offset:32768
	v_pk_fma_f32 v[166:167], v[224:225], v[84:85], v[166:167] op_sel:[0,1,0]
	ds_read_b128 v[138:141], v18 offset:32784
	v_pk_fma_f32 v[146:147], v[10:11], v[142:143], v[210:211] op_sel_hi:[0,1,1]
	v_pk_fma_f32 v[148:149], v[10:11], v[142:143], v[212:213] op_sel:[1,0,0]
	v_add_f32_dpp v166, v166, v166 quad_perm:[1,0,3,2] row_mask:0xf bank_mask:0xf bound_ctrl:1
	v_add_f32_dpp v167, v167, v167 quad_perm:[1,0,3,2] row_mask:0xf bank_mask:0xf bound_ctrl:1
	v_pk_fma_f32 v[150:151], v[12:13], v[142:143], v[214:215] op_sel_hi:[0,1,1]
	v_pk_fma_f32 v[152:153], v[12:13], v[142:143], v[216:217] op_sel:[1,0,0]
	v_pk_fma_f32 v[154:155], v[14:15], v[142:143], v[218:219] op_sel_hi:[0,1,1]
	v_add_f32_dpp v166, v166, v166 quad_perm:[2,3,0,1] row_mask:0xf bank_mask:0xf bound_ctrl:1
	v_add_f32_dpp v167, v167, v167 quad_perm:[2,3,0,1] row_mask:0xf bank_mask:0xf bound_ctrl:1
	v_pk_fma_f32 v[156:157], v[14:15], v[142:143], v[220:221] op_sel:[1,0,0]
	v_pk_fma_f32 v[158:159], v[16:17], v[142:143], v[222:223] op_sel_hi:[0,1,1]
	v_pk_fma_f32 v[160:161], v[16:17], v[142:143], v[224:225] op_sel:[1,0,0]
	v_add_f32_dpp v166, v166, v166 row_half_mirror row_mask:0xf bank_mask:0xf bound_ctrl:1
	v_add_f32_dpp v167, v167, v167 row_half_mirror row_mask:0xf bank_mask:0xf bound_ctrl:1
	s_waitcnt lgkmcnt(14)
	v_pk_fma_f32 v[146:147], v[86:87], v[166:167], v[146:147] op_sel_hi:[0,1,1]
	v_pk_fma_f32 v[148:149], v[86:87], v[166:167], v[148:149] op_sel:[1,0,0]
	s_waitcnt lgkmcnt(12)
	v_pk_mul_f32 v[170:171], v[146:147], v[94:95] op_sel_hi:[1,0]
	v_pk_fma_f32 v[150:151], v[88:89], v[166:167], v[150:151] op_sel_hi:[0,1,1]
	v_pk_fma_f32 v[170:171], v[148:149], v[94:95], v[170:171] op_sel:[0,1,0]
	v_pk_fma_f32 v[152:153], v[88:89], v[166:167], v[152:153] op_sel:[1,0,0]
	v_pk_fma_f32 v[170:171], v[150:151], v[96:97], v[170:171] op_sel_hi:[1,0,1]
	v_pk_fma_f32 v[154:155], v[90:91], v[166:167], v[154:155] op_sel_hi:[0,1,1]
	v_pk_fma_f32 v[170:171], v[152:153], v[96:97], v[170:171] op_sel:[0,1,0]
	v_pk_fma_f32 v[156:157], v[90:91], v[166:167], v[156:157] op_sel:[1,0,0]
	v_pk_fma_f32 v[170:171], v[154:155], v[98:99], v[170:171] op_sel_hi:[1,0,1]
	v_pk_fma_f32 v[158:159], v[92:93], v[166:167], v[158:159] op_sel_hi:[0,1,1]
	v_pk_fma_f32 v[170:171], v[156:157], v[98:99], v[170:171] op_sel:[0,1,0]
	v_pk_fma_f32 v[160:161], v[92:93], v[166:167], v[160:161] op_sel:[1,0,0]
	v_pk_fma_f32 v[170:171], v[158:159], v[100:101], v[170:171] op_sel_hi:[1,0,1]
	v_add_u32_e32 v18, s13, v18
	v_add_u32_e32 v19, s13, v19
	v_pk_fma_f32 v[170:171], v[160:161], v[100:101], v[170:171] op_sel:[0,1,0]
	s_waitcnt lgkmcnt(4)
; __device__ __forceinline__ void scan_chain(const Params& p, int l, int chain, unsigned char* lds) {
;     ...
;             auto ld = [&](int s, StepIn& I) {
;                 const int ts = dir == 0 ? s : 31 - s; const float* ap = arr + ts * 64 + 8 * cgp;
;                 I.w0 = *(const f32x4*)(ap); I.w1 = *(const f32x4*)(ap + 4); I.k0 = *(const f32x4*)(ap + 2048); I.k1 = *(const f32x4*)(ap + 2048 + 4);
;                 I.a0 = *(const f32x4*)(ap + 4096); I.a1 = *(const f32x4*)(ap + 4096 + 4); I.b0 = *(const f32x4*)(ap + 6144); I.b1 = *(const f32x4*)(ap + 6144 + 4);
;                 I.r0 = *(const f32x4*)(ap + 8192); I.r1 = *(const f32x4*)(ap + 8192 + 4);
;                 I.v0 = arr[5 * 2048 + ts * 64 + i0]; I.v1 = arr[5 * 2048 + ts * 64 + i1];
;             };
;             auto comp = [&](int s, const StepIn& I) {
;                 const int ts = dir == 0 ? s : 31 - s;
;                 const f32x2 w[4] = {{I.w0[0], I.w0[1]}, {I.w0[2], I.w0[3]}, {I.w1[0], I.w1[1]}, {I.w1[2], I.w1[3]}};
;                 const f32x2 k[4] = {{I.k0[0], I.k0[1]}, {I.k0[2], I.k0[3]}, {I.k1[0], I.k1[1]}, {I.k1[2], I.k1[3]}};
;                 const f32x2 a[4] = {{I.a0[0], I.a0[1]}, {I.a0[2], I.a0[3]}, {I.a1[0], I.a1[1]}, {I.a1[2], I.a1[3]}};
;                 const f32x2 bb[4] = {{I.b0[0], I.b0[1]}, {I.b0[2], I.b0[3]}, {I.b1[0], I.b1[1]}, {I.b1[2], I.b1[3]}};
;                 const f32x2 r[4] = {{I.r0[0], I.r0[1]}, {I.r0[2], I.r0[3]}, {I.r1[0], I.r1[1]}, {I.r1[2], I.r1[3]}};
;                 f32x2 d0 = S0[0] * a[0] + S0[1] * a[1], d0b = S0[2] * a[2] + S0[3] * a[3];
;                 f32x2 d1 = S1[0] * a[0] + S1[1] * a[1], d1b = S1[2] * a[2] + S1[3] * a[3];
;                 d0 += d0b; d1 += d1b;
;                 const float sa0 = sum8(d0.x + d0.y), sa1 = sum8(d1.x + d1.y);
; #pragma unroll
;                 for (int e = 0; e < 4; ++e) { S0[e] = S0[e] * w[e] + bb[e] * sa0 + k[e] * I.v0; S1[e] = S1[e] * w[e] + bb[e] * sa1 + k[e] * I.v1; }
;                 f32x2 y0 = S0[0] * r[0] + S0[1] * r[1], y0b = S0[2] * r[2] + S0[3] * r[3];
;                 f32x2 y1 = S1[0] * r[0] + S1[1] * r[1], y1b = S1[2] * r[2] + S1[3] * r[3];
;                 y0 += y0b; y1 += y1b;
;                 const float ya = sum8(y0.x + y0.y), yb = sum8(y1.x + y1.y);
;                 if (cgp == 0) { yl[ts * 64 + i0] = ya; yl[ts * 64 + i1] = yb; }
;             };
;             __builtin_amdgcn_s_setprio(3);
	v_pk_mul_f32 v[166:167], v[146:147], v[118:119] op_sel_hi:[1,0]
	ds_read_b128 v[78:81], v18 offset:16384
	v_pk_fma_f32 v[166:167], v[148:149], v[118:119], v[166:167] op_sel:[0,1,0]
	ds_read_b128 v[82:85], v18 offset:16400
	ds_read_b128 v[10:13], v18 offset:8192
	v_pk_fma_f32 v[166:167], v[150:151], v[120:121], v[166:167] op_sel_hi:[1,0,1]
	ds_read_b128 v[14:17], v18 offset:8208
	v_pk_fma_f32 v[166:167], v[152:153], v[120:121], v[166:167] op_sel:[0,1,0]
	ds_read2_b32 v[142:143], v19 offset1:8
	v_pk_fma_f32 v[166:167], v[154:155], v[122:123], v[166:167] op_sel_hi:[1,0,1]
	v_pk_fma_f32 v[166:167], v[156:157], v[122:123], v[166:167] op_sel:[0,1,0]
	ds_read_b128 v[86:89], v18 offset:24576
	ds_read_b128 v[90:93], v18 offset:24592
	v_pk_fma_f32 v[166:167], v[158:159], v[124:125], v[166:167] op_sel_hi:[1,0,1]
	ds_read_b128 v[94:97], v18 offset:32768
	v_pk_fma_f32 v[166:167], v[160:161], v[124:125], v[166:167] op_sel:[0,1,0]
	ds_read_b128 v[98:101], v18 offset:32784
	v_pk_mul_f32 v[210:211], v[110:111], v[144:145] op_sel_hi:[0,1]
	v_pk_mul_f32 v[212:213], v[110:111], v[144:145] op_sel:[1,0]
	v_add_f32_dpp v166, v166, v166 quad_perm:[1,0,3,2] row_mask:0xf bank_mask:0xf bound_ctrl:1
	v_add_f32_dpp v167, v167, v167 quad_perm:[1,0,3,2] row_mask:0xf bank_mask:0xf bound_ctrl:1
	v_pk_mul_f32 v[214:215], v[112:113], v[144:145] op_sel_hi:[0,1]
	v_pk_mul_f32 v[216:217], v[112:113], v[144:145] op_sel:[1,0]
	v_pk_mul_f32 v[218:219], v[114:115], v[144:145] op_sel_hi:[0,1]
	v_add_f32_dpp v166, v166, v166 quad_perm:[2,3,0,1] row_mask:0xf bank_mask:0xf bound_ctrl:1
	v_add_f32_dpp v167, v167, v167 quad_perm:[2,3,0,1] row_mask:0xf bank_mask:0xf bound_ctrl:1
	v_pk_mul_f32 v[220:221], v[114:115], v[144:145] op_sel:[1,0]
	v_pk_mul_f32 v[222:223], v[116:117], v[144:145] op_sel_hi:[0,1]
	v_pk_mul_f32 v[224:225], v[116:117], v[144:145] op_sel:[1,0]
	v_add_f32_dpp v166, v166, v166 row_half_mirror row_mask:0xf bank_mask:0xf bound_ctrl:1
	v_add_f32_dpp v167, v167, v167 row_half_mirror row_mask:0xf bank_mask:0xf bound_ctrl:1
	v_pk_fma_f32 v[210:211], v[146:147], v[102:103], v[210:211] op_sel_hi:[1,0,1]
	v_pk_fma_f32 v[212:213], v[148:149], v[102:103], v[212:213] op_sel:[0,1,0]
	v_pk_fma_f32 v[214:215], v[150:151], v[104:105], v[214:215] op_sel_hi:[1,0,1]
	v_pk_fma_f32 v[216:217], v[152:153], v[104:105], v[216:217] op_sel:[0,1,0]
	v_pk_fma_f32 v[218:219], v[154:155], v[106:107], v[218:219] op_sel_hi:[1,0,1]
	v_pk_fma_f32 v[220:221], v[156:157], v[106:107], v[220:221] op_sel:[0,1,0]
	v_pk_fma_f32 v[222:223], v[158:159], v[108:109], v[222:223] op_sel_hi:[1,0,1]
	v_pk_fma_f32 v[224:225], v[160:161], v[108:109], v[224:225] op_sel:[0,1,0]
	s_waitcnt lgkmcnt(11)
	v_pk_fma_f32 v[210:211], v[126:127], v[166:167], v[210:211] op_sel_hi:[0,1,1]
	v_pk_fma_f32 v[212:213], v[126:127], v[166:167], v[212:213] op_sel:[1,0,0]
	s_waitcnt lgkmcnt(9)
	v_pk_mul_f32 v[172:173], v[210:211], v[134:135] op_sel_hi:[1,0]
	v_pk_fma_f32 v[214:215], v[128:129], v[166:167], v[214:215] op_sel_hi:[0,1,1]
	v_pk_fma_f32 v[172:173], v[212:213], v[134:135], v[172:173] op_sel:[0,1,0]
	v_pk_fma_f32 v[216:217], v[128:129], v[166:167], v[216:217] op_sel:[1,0,0]
	v_pk_fma_f32 v[172:173], v[214:215], v[136:137], v[172:173] op_sel_hi:[1,0,1]
	v_pk_fma_f32 v[218:219], v[130:131], v[166:167], v[218:219] op_sel_hi:[0,1,1]
	v_pk_fma_f32 v[172:173], v[216:217], v[136:137], v[172:173] op_sel:[0,1,0]
	v_pk_fma_f32 v[220:221], v[130:131], v[166:167], v[220:221] op_sel:[1,0,0]
	v_pk_fma_f32 v[172:173], v[218:219], v[138:139], v[172:173] op_sel_hi:[1,0,1]
	v_pk_fma_f32 v[222:223], v[132:133], v[166:167], v[222:223] op_sel_hi:[0,1,1]
	v_pk_fma_f32 v[172:173], v[220:221], v[138:139], v[172:173] op_sel:[0,1,0]
	v_pk_fma_f32 v[224:225], v[132:133], v[166:167], v[224:225] op_sel:[1,0,0]
	v_pk_fma_f32 v[172:173], v[222:223], v[140:141], v[172:173] op_sel_hi:[1,0,1]
	v_pk_fma_f32 v[172:173], v[224:225], v[140:141], v[172:173] op_sel:[0,1,0]
	v_add_f32_dpp v168, v170, v170 row_half_mirror row_mask:0xf bank_mask:0x5 bound_ctrl:1
	v_add_f32_dpp v169, v171, v171 row_half_mirror row_mask:0xf bank_mask:0x5 bound_ctrl:1
	v_add_f32_dpp v168, v172, v172 row_half_mirror row_mask:0xf bank_mask:0xa bound_ctrl:1
	v_add_f32_dpp v169, v173, v173 row_half_mirror row_mask:0xf bank_mask:0xa bound_ctrl:1
	v_add_u32_e32 v18, s7, v18
	v_add_f32_dpp v168, v168, v168 quad_perm:[1,0,3,2] row_mask:0xf bank_mask:0xf bound_ctrl:1
	v_add_f32_dpp v169, v169, v169 quad_perm:[1,0,3,2] row_mask:0xf bank_mask:0xf bound_ctrl:1
	v_add_u32_e32 v19, s7, v19
	v_add_f32_dpp v168, v168, v168 quad_perm:[2,3,0,1] row_mask:0xf bank_mask:0xf bound_ctrl:1
	v_add_f32_dpp v169, v169, v169 quad_perm:[2,3,0,1] row_mask:0xf bank_mask:0xf bound_ctrl:1
	s_add_i32 s2, s2, -1
	s_cmp_lg_u32 s2, 0
	s_mov_b64 exec, s[14:15]
	ds_write2_b32 v20, v168, v169 offset1:8
	s_mov_b64 exec, -1
	v_add_u32_e32 v20, s12, v20
	s_cbranch_scc1 .Lscan_iter
	s_branch .LBB0_304
